# folded-pool-weight items read w_branch with nt loads (no L2 allocation beside the last in-projection round)
# baseline (speedup 1.0000x reference)
.LBB0_590:
	s_andn2_b64 vcc, exec, s[2:3]
	s_cbranch_vccnz .LBB0_571
	s_ashr_i32 s14, s0, 5
	v_mov_b32_e32 v2, v1
	s_lshl_b32 s2, s14, 7
	s_lshl_b32 s74, s2, 12
	s_add_u32 s74, s19, s74
	s_addc_u32 s75, s85, 0
	s_add_u32 s74, s74, 0x400000
	s_addc_u32 s75, s75, 0
	s_and_b32 s76, s0, 1
	s_lshl_b32 s76, s76, 11
	v_lshl_add_u32 v162, v1, 2, s76
	global_load_dword v34, v162, s[74:75] nt
	s_add_u32 s74, s74, 0x1000
	s_addc_u32 s75, s75, 0
	s_nop 1
	global_load_dword v35, v162, s[74:75] nt
	s_add_u32 s74, s74, 0x1000
	s_addc_u32 s75, s75, 0
	s_nop 1
	global_load_dword v36, v162, s[74:75] nt
	s_add_u32 s74, s74, 0x1000
	s_addc_u32 s75, s75, 0
	s_nop 1
	global_load_dword v37, v162, s[74:75] nt
	s_add_u32 s74, s74, 0x1000
	s_addc_u32 s75, s75, 0
	s_nop 1
	global_load_dword v38, v162, s[74:75] nt
	s_add_u32 s74, s74, 0x1000
	s_addc_u32 s75, s75, 0
	s_nop 1
	global_load_dword v39, v162, s[74:75] nt
	s_add_u32 s74, s74, 0x1000
	s_addc_u32 s75, s75, 0
	s_nop 1
	global_load_dword v40, v162, s[74:75] nt
	s_add_u32 s74, s74, 0x1000
	s_addc_u32 s75, s75, 0
	s_nop 1
	global_load_dword v41, v162, s[74:75] nt
	s_add_u32 s74, s74, 0x1000
	s_addc_u32 s75, s75, 0
	s_nop 1
	global_load_dword v42, v162, s[74:75] nt
	s_add_u32 s74, s74, 0x1000
	s_addc_u32 s75, s75, 0
	s_nop 1
	global_load_dword v43, v162, s[74:75] nt
	s_add_u32 s74, s74, 0x1000
	s_addc_u32 s75, s75, 0
	s_nop 1
	global_load_dword v44, v162, s[74:75] nt
	s_add_u32 s74, s74, 0x1000
	s_addc_u32 s75, s75, 0
	s_nop 1
	global_load_dword v45, v162, s[74:75] nt
	s_add_u32 s74, s74, 0x1000
	s_addc_u32 s75, s75, 0
	s_nop 1
	global_load_dword v46, v162, s[74:75] nt
	s_add_u32 s74, s74, 0x1000
	s_addc_u32 s75, s75, 0
	s_nop 1
	global_load_dword v47, v162, s[74:75] nt
	s_add_u32 s74, s74, 0x1000
	s_addc_u32 s75, s75, 0
	s_nop 1
	global_load_dword v48, v162, s[74:75] nt
	s_add_u32 s74, s74, 0x1000
	s_addc_u32 s75, s75, 0
	s_nop 1
	global_load_dword v49, v162, s[74:75] nt
	s_add_u32 s74, s74, 0x1000
	s_addc_u32 s75, s75, 0
	s_nop 1
	global_load_dword v50, v162, s[74:75] nt
	s_add_u32 s74, s74, 0x1000
	s_addc_u32 s75, s75, 0
	s_nop 1
	global_load_dword v51, v162, s[74:75] nt
	s_add_u32 s74, s74, 0x1000
	s_addc_u32 s75, s75, 0
	s_nop 1
	global_load_dword v52, v162, s[74:75] nt
	s_add_u32 s74, s74, 0x1000
	s_addc_u32 s75, s75, 0
	s_nop 1
	global_load_dword v53, v162, s[74:75] nt
	s_add_u32 s74, s74, 0x1000
	s_addc_u32 s75, s75, 0
	s_nop 1
	global_load_dword v54, v162, s[74:75] nt
	s_add_u32 s74, s74, 0x1000
	s_addc_u32 s75, s75, 0
	s_nop 1
	global_load_dword v55, v162, s[74:75] nt
	s_add_u32 s74, s74, 0x1000
	s_addc_u32 s75, s75, 0
	s_nop 1
	global_load_dword v56, v162, s[74:75] nt
	s_add_u32 s74, s74, 0x1000
	s_addc_u32 s75, s75, 0
	s_nop 1
	global_load_dword v57, v162, s[74:75] nt
	s_add_u32 s74, s74, 0x1000
	s_addc_u32 s75, s75, 0
	s_nop 1
	global_load_dword v58, v162, s[74:75] nt
	s_add_u32 s74, s74, 0x1000
	s_addc_u32 s75, s75, 0
	s_nop 1
	global_load_dword v59, v162, s[74:75] nt
	s_add_u32 s74, s74, 0x1000
	s_addc_u32 s75, s75, 0
	s_nop 1
	global_load_dword v60, v162, s[74:75] nt
	s_add_u32 s74, s74, 0x1000
	s_addc_u32 s75, s75, 0
	s_nop 1
	global_load_dword v61, v162, s[74:75] nt
	s_add_u32 s74, s74, 0x1000
	s_addc_u32 s75, s75, 0
	s_nop 1
	global_load_dword v62, v162, s[74:75] nt
	s_add_u32 s74, s74, 0x1000
	s_addc_u32 s75, s75, 0
	s_nop 1
	global_load_dword v63, v162, s[74:75] nt
	s_add_u32 s74, s74, 0x1000
	s_addc_u32 s75, s75, 0
	s_nop 1
	global_load_dword v64, v162, s[74:75] nt
	s_add_u32 s74, s74, 0x1000
	s_addc_u32 s75, s75, 0
	s_nop 1
	global_load_dword v65, v162, s[74:75] nt
	s_add_u32 s74, s74, 0x1000
	s_addc_u32 s75, s75, 0
	s_nop 1
	s_waitcnt vmcnt(31)
	global_load_dword v66, v162, s[74:75] nt
	s_add_u32 s74, s74, 0x1000
	s_addc_u32 s75, s75, 0
	s_nop 1
	global_load_dword v67, v162, s[74:75] nt
	s_add_u32 s74, s74, 0x1000
	s_addc_u32 s75, s75, 0
	s_nop 1
	global_load_dword v68, v162, s[74:75] nt
	s_add_u32 s74, s74, 0x1000
	s_addc_u32 s75, s75, 0
	s_nop 1
	global_load_dword v69, v162, s[74:75] nt
	s_add_u32 s74, s74, 0x1000
	s_addc_u32 s75, s75, 0
	s_nop 1
	global_load_dword v70, v162, s[74:75] nt
	s_add_u32 s74, s74, 0x1000
	s_addc_u32 s75, s75, 0
	s_nop 1
	global_load_dword v71, v162, s[74:75] nt
	s_add_u32 s74, s74, 0x1000
	s_addc_u32 s75, s75, 0
	s_nop 1
	global_load_dword v72, v162, s[74:75] nt
	s_add_u32 s74, s74, 0x1000
	s_addc_u32 s75, s75, 0
	s_nop 1
	global_load_dword v73, v162, s[74:75] nt
	s_add_u32 s74, s74, 0x1000
	s_addc_u32 s75, s75, 0
	s_nop 1
	global_load_dword v74, v162, s[74:75] nt
	s_add_u32 s74, s74, 0x1000
	s_addc_u32 s75, s75, 0
	s_nop 1
	global_load_dword v75, v162, s[74:75] nt
	s_add_u32 s74, s74, 0x1000
	s_addc_u32 s75, s75, 0
	s_nop 1
	global_load_dword v76, v162, s[74:75] nt
	s_add_u32 s74, s74, 0x1000
	s_addc_u32 s75, s75, 0
	s_nop 1
	global_load_dword v77, v162, s[74:75] nt
	s_add_u32 s74, s74, 0x1000
	s_addc_u32 s75, s75, 0
	s_nop 1
	global_load_dword v78, v162, s[74:75] nt
	s_add_u32 s74, s74, 0x1000
	s_addc_u32 s75, s75, 0
	s_nop 1
	global_load_dword v79, v162, s[74:75] nt
	s_add_u32 s74, s74, 0x1000
	s_addc_u32 s75, s75, 0
	s_nop 1
	global_load_dword v80, v162, s[74:75] nt
	s_add_u32 s74, s74, 0x1000
	s_addc_u32 s75, s75, 0
	s_nop 1
	global_load_dword v81, v162, s[74:75] nt
	s_add_u32 s74, s74, 0x1000
	s_addc_u32 s75, s75, 0
	s_nop 1
	global_load_dword v82, v162, s[74:75] nt
	s_add_u32 s74, s74, 0x1000
	s_addc_u32 s75, s75, 0
	s_nop 1
	global_load_dword v83, v162, s[74:75] nt
	s_add_u32 s74, s74, 0x1000
	s_addc_u32 s75, s75, 0
	s_nop 1
	global_load_dword v84, v162, s[74:75] nt
	s_add_u32 s74, s74, 0x1000
	s_addc_u32 s75, s75, 0
	s_nop 1
	global_load_dword v85, v162, s[74:75] nt
	s_add_u32 s74, s74, 0x1000
	s_addc_u32 s75, s75, 0
	s_nop 1
	global_load_dword v86, v162, s[74:75] nt
	s_add_u32 s74, s74, 0x1000
	s_addc_u32 s75, s75, 0
	s_nop 1
	global_load_dword v87, v162, s[74:75] nt
	s_add_u32 s74, s74, 0x1000
	s_addc_u32 s75, s75, 0
	s_nop 1
	global_load_dword v88, v162, s[74:75] nt
	s_add_u32 s74, s74, 0x1000
	s_addc_u32 s75, s75, 0
	s_nop 1
	global_load_dword v89, v162, s[74:75] nt
	s_add_u32 s74, s74, 0x1000
	s_addc_u32 s75, s75, 0
	s_nop 1
	global_load_dword v90, v162, s[74:75] nt
	s_add_u32 s74, s74, 0x1000
	s_addc_u32 s75, s75, 0
	s_nop 1
	global_load_dword v91, v162, s[74:75] nt
	s_add_u32 s74, s74, 0x1000
	s_addc_u32 s75, s75, 0
	s_nop 1
	global_load_dword v92, v162, s[74:75] nt
	s_add_u32 s74, s74, 0x1000
	s_addc_u32 s75, s75, 0
	s_nop 1
	global_load_dword v93, v162, s[74:75] nt
	s_add_u32 s74, s74, 0x1000
	s_addc_u32 s75, s75, 0
	s_nop 1
	global_load_dword v94, v162, s[74:75] nt
	s_add_u32 s74, s74, 0x1000
	s_addc_u32 s75, s75, 0
	s_nop 1
	global_load_dword v95, v162, s[74:75] nt
	s_add_u32 s74, s74, 0x1000
	s_addc_u32 s75, s75, 0
	s_nop 1
	global_load_dword v96, v162, s[74:75] nt
	s_add_u32 s74, s74, 0x1000
	s_addc_u32 s75, s75, 0
	s_nop 1
	global_load_dword v97, v162, s[74:75] nt
	s_add_u32 s74, s74, 0x1000
	s_addc_u32 s75, s75, 0
	s_nop 1
	s_waitcnt vmcnt(31)
	global_load_dword v98, v162, s[74:75] nt
	s_add_u32 s74, s74, 0x1000
	s_addc_u32 s75, s75, 0
	s_nop 1
	global_load_dword v99, v162, s[74:75] nt
	s_add_u32 s74, s74, 0x1000
	s_addc_u32 s75, s75, 0
	s_nop 1
	global_load_dword v100, v162, s[74:75] nt
	s_add_u32 s74, s74, 0x1000
	s_addc_u32 s75, s75, 0
	s_nop 1
	global_load_dword v101, v162, s[74:75] nt
	s_add_u32 s74, s74, 0x1000
	s_addc_u32 s75, s75, 0
	s_nop 1
	global_load_dword v102, v162, s[74:75] nt
	s_add_u32 s74, s74, 0x1000
	s_addc_u32 s75, s75, 0
	s_nop 1
	global_load_dword v103, v162, s[74:75] nt
	s_add_u32 s74, s74, 0x1000
	s_addc_u32 s75, s75, 0
	s_nop 1
	global_load_dword v104, v162, s[74:75] nt
	s_add_u32 s74, s74, 0x1000
	s_addc_u32 s75, s75, 0
	s_nop 1
	global_load_dword v105, v162, s[74:75] nt
	s_add_u32 s74, s74, 0x1000
	s_addc_u32 s75, s75, 0
	s_nop 1
	global_load_dword v106, v162, s[74:75] nt
	s_add_u32 s74, s74, 0x1000
	s_addc_u32 s75, s75, 0
	s_nop 1
	global_load_dword v107, v162, s[74:75] nt
	s_add_u32 s74, s74, 0x1000
	s_addc_u32 s75, s75, 0
	s_nop 1
	global_load_dword v108, v162, s[74:75] nt
	s_add_u32 s74, s74, 0x1000
	s_addc_u32 s75, s75, 0
	s_nop 1
	global_load_dword v109, v162, s[74:75] nt
	s_add_u32 s74, s74, 0x1000
	s_addc_u32 s75, s75, 0
	s_nop 1
	global_load_dword v110, v162, s[74:75] nt
	s_add_u32 s74, s74, 0x1000
	s_addc_u32 s75, s75, 0
	s_nop 1
	global_load_dword v111, v162, s[74:75] nt
	s_add_u32 s74, s74, 0x1000
	s_addc_u32 s75, s75, 0
	s_nop 1
	global_load_dword v112, v162, s[74:75] nt
	s_add_u32 s74, s74, 0x1000
	s_addc_u32 s75, s75, 0
	s_nop 1
	global_load_dword v113, v162, s[74:75] nt
	s_add_u32 s74, s74, 0x1000
	s_addc_u32 s75, s75, 0
	s_nop 1
	global_load_dword v114, v162, s[74:75] nt
	s_add_u32 s74, s74, 0x1000
	s_addc_u32 s75, s75, 0
	s_nop 1
	global_load_dword v115, v162, s[74:75] nt
	s_add_u32 s74, s74, 0x1000
	s_addc_u32 s75, s75, 0
	s_nop 1
	global_load_dword v116, v162, s[74:75] nt
	s_add_u32 s74, s74, 0x1000
	s_addc_u32 s75, s75, 0
	s_nop 1
	global_load_dword v117, v162, s[74:75] nt
	s_add_u32 s74, s74, 0x1000
	s_addc_u32 s75, s75, 0
	s_nop 1
	global_load_dword v118, v162, s[74:75] nt
	s_add_u32 s74, s74, 0x1000
	s_addc_u32 s75, s75, 0
	s_nop 1
	global_load_dword v119, v162, s[74:75] nt
	s_add_u32 s74, s74, 0x1000
	s_addc_u32 s75, s75, 0
	s_nop 1
	global_load_dword v120, v162, s[74:75] nt
	s_add_u32 s74, s74, 0x1000
	s_addc_u32 s75, s75, 0
	s_nop 1
	global_load_dword v121, v162, s[74:75] nt
	s_add_u32 s74, s74, 0x1000
	s_addc_u32 s75, s75, 0
	s_nop 1
	global_load_dword v122, v162, s[74:75] nt
	s_add_u32 s74, s74, 0x1000
	s_addc_u32 s75, s75, 0
	s_nop 1
	global_load_dword v123, v162, s[74:75] nt
	s_add_u32 s74, s74, 0x1000
	s_addc_u32 s75, s75, 0
	s_nop 1
	global_load_dword v124, v162, s[74:75] nt
	s_add_u32 s74, s74, 0x1000
	s_addc_u32 s75, s75, 0
	s_nop 1
	global_load_dword v125, v162, s[74:75] nt
	s_add_u32 s74, s74, 0x1000
	s_addc_u32 s75, s75, 0
	s_nop 1
	global_load_dword v126, v162, s[74:75] nt
	s_add_u32 s74, s74, 0x1000
	s_addc_u32 s75, s75, 0
	s_nop 1
	global_load_dword v127, v162, s[74:75] nt
	s_add_u32 s74, s74, 0x1000
	s_addc_u32 s75, s75, 0
	s_nop 1
	global_load_dword v128, v162, s[74:75] nt
	s_add_u32 s74, s74, 0x1000
	s_addc_u32 s75, s75, 0
	s_nop 1
	global_load_dword v129, v162, s[74:75] nt
	s_add_u32 s74, s74, 0x1000
	s_addc_u32 s75, s75, 0
	s_nop 1
	s_waitcnt vmcnt(31)
	global_load_dword v130, v162, s[74:75] nt
	s_add_u32 s74, s74, 0x1000
	s_addc_u32 s75, s75, 0
	s_nop 1
	global_load_dword v131, v162, s[74:75] nt
	s_add_u32 s74, s74, 0x1000
	s_addc_u32 s75, s75, 0
	s_nop 1
	global_load_dword v132, v162, s[74:75] nt
	s_add_u32 s74, s74, 0x1000
	s_addc_u32 s75, s75, 0
	s_nop 1
	global_load_dword v133, v162, s[74:75] nt
	s_add_u32 s74, s74, 0x1000
	s_addc_u32 s75, s75, 0
	s_nop 1
	global_load_dword v134, v162, s[74:75] nt
	s_add_u32 s74, s74, 0x1000
	s_addc_u32 s75, s75, 0
	s_nop 1
	global_load_dword v135, v162, s[74:75] nt
	s_add_u32 s74, s74, 0x1000
	s_addc_u32 s75, s75, 0
	s_nop 1
	global_load_dword v136, v162, s[74:75] nt
	s_add_u32 s74, s74, 0x1000
	s_addc_u32 s75, s75, 0
	s_nop 1
	global_load_dword v137, v162, s[74:75] nt
	s_add_u32 s74, s74, 0x1000
	s_addc_u32 s75, s75, 0
	s_nop 1
	global_load_dword v138, v162, s[74:75] nt
	s_add_u32 s74, s74, 0x1000
	s_addc_u32 s75, s75, 0
	s_nop 1
	global_load_dword v139, v162, s[74:75] nt
	s_add_u32 s74, s74, 0x1000
	s_addc_u32 s75, s75, 0
	s_nop 1
	global_load_dword v140, v162, s[74:75] nt
	s_add_u32 s74, s74, 0x1000
	s_addc_u32 s75, s75, 0
	s_nop 1
	global_load_dword v141, v162, s[74:75] nt
	s_add_u32 s74, s74, 0x1000
	s_addc_u32 s75, s75, 0
	s_nop 1
	global_load_dword v142, v162, s[74:75] nt
	s_add_u32 s74, s74, 0x1000
	s_addc_u32 s75, s75, 0
	s_nop 1
	global_load_dword v143, v162, s[74:75] nt
	s_add_u32 s74, s74, 0x1000
	s_addc_u32 s75, s75, 0
	s_nop 1
	global_load_dword v144, v162, s[74:75] nt
	s_add_u32 s74, s74, 0x1000
	s_addc_u32 s75, s75, 0
	s_nop 1
	global_load_dword v145, v162, s[74:75] nt
	s_add_u32 s74, s74, 0x1000
	s_addc_u32 s75, s75, 0
	s_nop 1
	global_load_dword v146, v162, s[74:75] nt
	s_add_u32 s74, s74, 0x1000
	s_addc_u32 s75, s75, 0
	s_nop 1
	global_load_dword v147, v162, s[74:75] nt
	s_add_u32 s74, s74, 0x1000
	s_addc_u32 s75, s75, 0
	s_nop 1
	global_load_dword v148, v162, s[74:75] nt
	s_add_u32 s74, s74, 0x1000
	s_addc_u32 s75, s75, 0
	s_nop 1
	global_load_dword v149, v162, s[74:75] nt
	s_add_u32 s74, s74, 0x1000
	s_addc_u32 s75, s75, 0
	s_nop 1
	global_load_dword v150, v162, s[74:75] nt
	s_add_u32 s74, s74, 0x1000
	s_addc_u32 s75, s75, 0
	s_nop 1
	global_load_dword v151, v162, s[74:75] nt
	s_add_u32 s74, s74, 0x1000
	s_addc_u32 s75, s75, 0
	s_nop 1
	global_load_dword v152, v162, s[74:75] nt
	s_add_u32 s74, s74, 0x1000
	s_addc_u32 s75, s75, 0
	s_nop 1
	global_load_dword v153, v162, s[74:75] nt
	s_add_u32 s74, s74, 0x1000
	s_addc_u32 s75, s75, 0
	s_nop 1
	global_load_dword v154, v162, s[74:75] nt
	s_add_u32 s74, s74, 0x1000
	s_addc_u32 s75, s75, 0
	s_nop 1
	global_load_dword v155, v162, s[74:75] nt
	s_add_u32 s74, s74, 0x1000
	s_addc_u32 s75, s75, 0
	s_nop 1
	global_load_dword v156, v162, s[74:75] nt
	s_add_u32 s74, s74, 0x1000
	s_addc_u32 s75, s75, 0
	s_nop 1
	global_load_dword v157, v162, s[74:75] nt
	s_add_u32 s74, s74, 0x1000
	s_addc_u32 s75, s75, 0
	s_nop 1
	global_load_dword v158, v162, s[74:75] nt
	s_add_u32 s74, s74, 0x1000
	s_addc_u32 s75, s75, 0
	s_nop 1
	global_load_dword v159, v162, s[74:75] nt
	s_add_u32 s74, s74, 0x1000
	s_addc_u32 s75, s75, 0
	s_nop 1
	global_load_dword v160, v162, s[74:75] nt
	s_add_u32 s74, s74, 0x1000
	s_addc_u32 s75, s75, 0
	s_nop 1
	global_load_dword v161, v162, s[74:75] nt
	s_add_u32 s74, s74, 0x1000
	s_addc_u32 s75, s75, 0
	s_nop 1
	s_movk_i32 s12, 0x400
	s_bfe_u32 s48, s0, 0x40001
	s_ashr_i32 s3, s2, 31
	v_cmp_gt_i32_e32 vcc, s12, v2
	s_and_saveexec_b64 s[12:13], vcc
	s_movk_i32 vcc_lo, 0x1ff
	s_cbranch_execz .LBB0_599
	s_add_i32 s14, s14, s81
	s_ashr_i32 s15, s14, 31
	s_lshl_b64 s[14:15], s[14:15], 7
	s_lshl_b32 s30, s48, 3
	s_or_b32 s14, s14, s30
	v_max_i32_e32 v3, 0x200, v2
	v_and_or_b32 v4, v2, 7, s14
	v_mov_b32_e32 v5, s15
	v_sub_u32_e32 v3, v3, v2
	v_lshlrev_b64 v[4:5], 9, v[4:5]
	v_add_u32_e32 v6, 0x1ff, v3
	s_add_i32 s86, s2, s84
	v_lshl_add_u64 v[4:5], s[40:41], 0, v[4:5]
	v_cmp_lt_u32_e32 vcc, vcc_lo, v6
	s_mov_b64 s[30:31], -1
	v_mov_b32_e32 v3, v2
	s_and_saveexec_b64 s[14:15], vcc
	s_cbranch_execz .LBB0_596
	v_lshrrev_b32_e32 v3, 9, v6
	v_add_u32_e32 v8, 1, v3
	v_and_b32_e32 v9, 0xfffffe, v8
	v_add_u32_e32 v3, 0x200, v2
	s_mov_b32 s87, s86
	v_lshl_add_u32 v10, v2, 2, 0
	s_mov_b64 s[30:31], 0
	v_mov_b32_e32 v11, v9
	v_mov_b64_e32 v[6:7], v[2:3]
